# w_out and down GEMMs also use the whole-line LDS-DMA image
# speedup vs baseline: 1.0026x; 1.0026x over previous
; template <class Epi, class Sched, bool ALIGN_EPI = false, bool SP2 = false>
; __device__ __forceinline__ void gemm_phase(PG8_LAS unsigned char* lds, const Gemm g, const Sched& S, const Epi& E) {
;     ...
;     for (int i = 0; i < 2; ++i) { int R, C; stage_rc(tid * 16 + i * 8192, R, C); const int Rb = Epi::PERM ? ((R & ~31) + perm32(R & 31)) : R;
;         voffA[i] = (unsigned)(R * K + C) * 2u; voffB[i] = (unsigned)(Rb * K + C) * 2u; }
; __global__ void __launch_bounds__(NTHREADS, 2) fwd_kernel(Params p) {
;     ...
;     if (RUN(7)) {
;         pg8::Gemm g{(const bf16_t*)(ws + WS_MIXED), (const bf16_t*)(ws + WS_WOUT), T, DM, DM}; pg8::StaticOrder S; S.init(T, DM, G, cid);
;         EpiPlainBf16 E{(bf16_t*)(ws + WS_BR1), DM};
;         pg8::gemm_phase<EpiPlainBf16, pg8::StaticOrder, true, true>(ring, g, S, E);
.LBB0_732:
	v_readlane_b32 s4, v246, 12
	s_cmp_lt_i32 s4, 8
	s_cselect_b64 s[2:3], -1, 0
	s_and_b64 s[0:1], s[2:3], s[0:1]
	s_andn2_b64 vcc, exec, s[0:1]
	v_readlane_b32 s5, v246, 13
	v_readlane_b32 s6, v246, 14
	v_readlane_b32 s7, v246, 15
	s_cbranch_vccnz .LBB0_757
	v_lshrrev_b32_e32 v238, 3, v144
	v_and_b32_e32 v239, 7, v144
	v_and_b32_e32 v240, 7, v238
	v_xor_b32_e32 v239, v239, v240
	v_lshlrev_b32_e32 v239, 4, v239
	v_lshl_or_b32 v240, v238, 12, v239
	v_add_u32_e32 v241, 0x40000, v240
	v_and_b32_e32 v242, 31, v238
	v_bfe_u32 v243, v242, 2, 2
	v_lshlrev_b32_e32 v243, 3, v243
	v_lshrrev_b32_e32 v230, 4, v242
	v_lshl_or_b32 v243, v230, 2, v243
	v_and_b32_e32 v230, 3, v242
	v_or_b32_e32 v243, v243, v230
	v_and_b32_e32 v230, 32, v238
	v_or_b32_e32 v243, v243, v230
	v_lshl_or_b32 v238, v243, 12, v239
	v_add_u32_e32 v239, 0x40000, v238
	v_readlane_b32 s0, v246, 0
	s_cmpk_gt_i32 s0, 0x3ff
	v_readfirstlane_b32 s12, v144
	v_readlane_b32 s1, v246, 1
	s_cbranch_scc1 .LBB0_757
	v_readlane_b32 s0, v246, 0
	s_ashr_i32 s33, s0, 31
	s_mov_b32 s4, s0
	s_lshr_b32 s0, s33, 29
	s_add_i32 s5, s4, s0
	s_and_b32 s0, s5, -8
	s_sub_i32 s6, s4, s0
	s_cmp_gt_i32 s6, -1
	v_readlane_b32 s1, v246, 1
	s_cbranch_scc0 .LBB0_736
	s_lshl_b32 s4, s6, 7
	s_cbranch_execz .LBB0_737
	s_branch .LBB0_738

; #define PG8_STAGE(bufoff, gbase, voff) do { _Pragma("unroll") for (int _i = 0; _i < 2; ++_i) \
;         __builtin_amdgcn_global_load_lds((const unsigned*)((const char*)(gbase) + (voff)[_i]), (PG8_LAS unsigned*)(lds + (bufoff) + ldsw + _i * 8192), 16, 0, 0); } while (0)
; #define PG8_WAIT_V(n) asm volatile("s_waitcnt vmcnt(" #n ")" ::: "memory")
; #define PG8_BAR __builtin_amdgcn_s_barrier()
;     __device__ bool next(int i, pg8::Unit& u) const { if (!base.next(i >> 1, u)) return false; u.seg = i & 1; return true; }
; template <class Epi, class Sched, bool ALIGN_EPI = false, bool SP2 = false>
; __device__ __forceinline__ void gemm_phase(PG8_LAS unsigned char* lds, const Gemm g, const Sched& S, const Epi& E) {
;     ...
;     for (int i = 0; i < 2; ++i) { int R, C; stage_rc(tid * 16 + i * 8192, R, C); const int Rb = Epi::PERM ? ((R & ~31) + perm32(R & 31)) : R;
;         voffA[i] = (unsigned)(R * K + C) * 2u; voffB[i] = (unsigned)(Rb * K + C) * 2u; }
;     const size_t kstep = (size_t)(BK * 2);
;     const size_t hstep = (size_t)HALF * K * 2;
;     const size_t tstep = 2 * hstep;
;     const unsigned ldsw = (unsigned)wid * 1024u;
;     const int aoff = lds_byte(wr * 64 + fr, fq * 8), boff = lds_byte(wc * 32 + fr, fq * 8);
;     ...
;     Unit cur, nxt; int ui = 0;
;     if (!S.next(0, cur)) return;
;     f32x4 acc[2][2][4][2];
; #pragma unroll
;     for (int a = 0; a < 2; ++a)
; #pragma unroll
;         for (int b = 0; b < 2; ++b)
; #pragma unroll
;             for (int m = 0; m < 4; ++m)
; #pragma unroll
;                 for (int n = 0; n < 2; ++n) acc[a][b][m][n] = (f32x4){0.f, 0.f, 0.f, 0.f};
;     bf16x8 At[4][2], B0[2][2], B1[2][2];
;     const char* cA = (const char*)(cur.seg ? g.A2 : g.A) + (size_t)cur.pm * tstep; const char* cB = (const char*)(cur.seg ? g.Bt2 : g.Bt) + (size_t)cur.pn * tstep;
;     S.a_ready(cur);
;     if constexpr (SP2) {
;         PG8_STAGE(PG8_SB(0, 0), cB, voffB); PG8_STAGE(PG8_SB(0, 1), cB + hstep, voffB); PG8_STAGE(PG8_SA(0, 0), cA, voffA); PG8_STAGE(PG8_SA(0, 1), cA + hstep, voffA);
;         if (wr == 1) PG8_BAR;
;         PG8_WAIT_V(2); PG8_BAR;
;         PG8_STAGE(PG8_SB(1, 0), cB + kstep, voffB); PG8_STAGE(PG8_SA(1, 0), cA + kstep, voffA); PG8_STAGE(PG8_SB(1, 1), cB + hstep + kstep, voffB);
;         PG8_WAIT_V(6); PG8_BAR;
.LBB0_738:
	s_ashr_i32 s0, s5, 3
	v_readlane_b32 s6, v246, 10
	v_readlane_b32 s7, v246, 11
	s_add_u32 s35, s6, 0x1c800000
	s_addc_u32 s44, s7, 0
	s_add_u32 s45, s6, 0x3600000
	s_addc_u32 s46, s7, 0
	s_add_i32 s0, s4, s0
	s_ashr_i32 s4, s0, 31
	s_lshr_b32 s4, s4, 26
	s_add_i32 s4, s0, s4
	s_ashr_i32 s5, s4, 6
	s_andn2_b32 s4, s4, 63
	s_waitcnt lgkmcnt(0)
	v_lshrrev_b32_e32 v2, 1, v144
	s_sub_i32 s4, s0, s4
	s_waitcnt vmcnt(0)
	v_and_b32_e32 v11, 24, v2
	v_lshrrev_b32_e32 v2, 5, v144
	s_bfe_i32 s0, s4, 0x80000
	v_and_b32_e32 v2, 4, v2
	v_bfe_u32 v3, v144, 2, 2
	s_bfe_u32 s0, s0, 0x3000c
	v_lshlrev_b32_e32 v0, 4, v144
	v_and_b32_e32 v1, 32, v144
	v_bfe_u32 v10, v144, 2, 4
	v_or3_b32 v2, v2, v3, v11
	v_lshrrev_b32_e32 v3, 3, v144
	s_movk_i32 s1, 0x70
	s_add_i32 s6, s4, s0
	v_bitop3_b32 v8, v0, v1, 48 bitop3:0x6c
	v_and_b32_e32 v9, 64, v144
	v_and_or_b32 v4, v3, s1, v10
	s_movk_i32 s1, 0x60
	v_add_u32_e32 v12, 0x2000, v0
	s_bfe_i32 s0, s6, 0x80000
	s_and_b32 s6, s6, 0xf8
	v_or_b32_e32 v1, v8, v9
	v_and_or_b32 v3, v3, s1, v2
	v_lshrrev_b32_e32 v0, 7, v12
	s_movk_i32 s1, 0xf0
	s_sub_i32 s4, s4, s6
	v_lshl_or_b32 v130, v3, 12, v1
	v_mov_b32_e32 v130, v238
	v_and_or_b32 v3, v0, s1, v10
	s_movk_i32 s1, 0xe0
	s_lshl_b32 s5, s5, 3
	s_sext_i32_i16 s0, s0
	s_sext_i32_i8 s4, s4
	v_and_or_b32 v0, v0, s1, v2
	s_lshr_b32 s1, s12, 8
	s_lshr_b32 s0, s0, 3
	s_add_i32 s30, s5, s4
	s_lshr_b32 s10, s12, 6
	s_ashr_i32 s31, s30, 31
	s_bfe_i64 s[6:7], s[0:1], 0x100000
	s_lshl_b32 s47, s10, 10
	s_lshl_b64 s[4:5], s[30:31], 20
	s_lshl_b64 s[6:7], s[6:7], 20
	s_add_u32 s40, s45, s6
	s_addc_u32 s41, s46, s7
	s_add_i32 s31, s47, 0
	s_add_i32 m0, s31, 0x10000
	v_lshl_or_b32 v134, v0, 12, v1
	v_mov_b32_e32 v134, v239
	global_load_lds_dwordx4 v130, s[40:41]
	s_add_i32 m0, s31, 0x12000
	s_add_u32 s6, s40, 0x80000
	global_load_lds_dwordx4 v134, s[40:41]
	s_addc_u32 s7, s41, 0
	s_add_i32 m0, s31, 0x14000
	v_lshl_or_b32 v128, v4, 12, v1
	v_mov_b32_e32 v128, v240
	global_load_lds_dwordx4 v130, s[6:7]
	s_add_i32 m0, s31, 0x16000
	s_add_u32 s38, s35, s4
	s_addc_u32 s39, s44, s5
	s_add_i32 s48, s31, 0x2000
	global_load_lds_dwordx4 v134, s[6:7]
	s_mov_b32 m0, s31
	s_add_u32 s4, s38, 0x80000
	v_lshl_or_b32 v132, v3, 12, v1
	v_mov_b32_e32 v132, v241
	global_load_lds_dwordx4 v128, s[38:39]
	s_mov_b32 m0, s48
	s_addc_u32 s5, s39, 0
	s_add_i32 s49, s31, 0x4000
	global_load_lds_dwordx4 v132, s[38:39]
	s_mov_b32 m0, s49
	s_add_i32 s50, s31, 0x6000
	global_load_lds_dwordx4 v128, s[4:5]
	s_mov_b32 m0, s50
	v_mov_b32_e32 v131, 0
	global_load_lds_dwordx4 v132, s[4:5]
	v_mov_b32_e32 v135, v131
	v_mov_b32_e32 v129, v131
	v_mov_b32_e32 v133, v131
	s_cmp_eq_u32 s1, 1
	s_mov_b32 s51, 0
	v_lshl_add_u64 v[6:7], s[40:41], 0, v[130:131]
	v_lshl_add_u64 v[2:3], s[40:41], 0, v[134:135]
	s_mov_b64 s[4:5], 0x80000
	v_lshl_add_u64 v[0:1], s[38:39], 0, v[128:129]
	s_cselect_b64 s[6:7], -1, 0
	s_cmp_lg_u32 s1, 1
	v_lshl_add_u64 v[4:5], s[38:39], 0, v[132:133]
	s_cbranch_scc1 .LBB0_740
	s_barrier
.LBB0_740:
	v_readlane_b32 s8, v246, 10
	v_readlane_b32 s9, v246, 11
	s_add_u32 s8, s8, 0x10800000
	s_addc_u32 s9, s9, 0
	s_lshl_b32 s10, s10, 5
	s_and_b32 s18, s10, 0x60
	s_mov_b64 s[10:11], 0x80
	s_add_i32 m0, s31, 0x18000
	v_lshl_add_u64 v[6:7], v[6:7], 0, s[10:11]
	s_lshl_b32 s13, s1, 13
	s_lshl_b32 s19, s18, 7
	s_waitcnt vmcnt(2)
	s_barrier
	global_load_lds_dwordx4 v[6:7], off
	v_lshl_add_u64 v[2:3], v[2:3], 0, s[10:11]
	s_add_i32 m0, s31, 0x1a000
	s_add_i32 s52, s31, 0x8000
	s_add_i32 s53, s31, 0xa000
	global_load_lds_dwordx4 v[2:3], off
	v_lshl_add_u64 v[0:1], v[0:1], 0, s[10:11]
	s_mov_b32 m0, s52
	s_add_u32 s14, s40, 0x80080
	global_load_lds_dwordx4 v[0:1], off
	v_lshl_add_u64 v[0:1], v[4:5], 0, s[10:11]
	s_mov_b32 m0, s53
	s_addc_u32 s15, s41, 0
	global_load_lds_dwordx4 v[0:1], off
	s_add_i32 m0, s31, 0x1c000
	v_lshl_add_u64 v[0:1], s[14:15], 0, v[130:131]
	global_load_lds_dwordx4 v[0:1], off
	v_lshl_add_u64 v[0:1], s[14:15], 0, v[134:135]
	s_add_i32 m0, s31, 0x1e000
	s_sext_i32_i8 s61, s0
	global_load_lds_dwordx4 v[0:1], off
	v_and_b32_e32 v0, 15, v144
	v_lshlrev_b32_e32 v1, 1, v11
	v_lshlrev_b32_e32 v2, 2, v144
	v_lshlrev_b32_e32 v3, 6, v144
	s_movk_i32 s0, 0x3c0
	v_lshl_or_b32 v145, s1, 6, v0
	v_lshl_or_b32 v0, v0, 6, v1
	v_and_b32_e32 v2, 32, v2
	v_and_or_b32 v1, v3, s0, v1
	v_bitop3_b32 v148, s19, v1, v2 bitop3:0xf6
	v_lshlrev_b32_e32 v1, 9, v144
	v_bitop3_b32 v0, v0, s13, v2 bitop3:0xde
	v_and_b32_e32 v1, 0x70000, v1
	v_lshlrev_b32_e32 v2, 12, v10
	v_or3_b32 v1, v8, v1, v2
	v_add_u32_e32 v136, v1, v9
	v_mov_b32_e32 v136, v240
	v_lshlrev_b32_e32 v1, 5, v12
	s_waitcnt vmcnt(6)
	s_cmpk_lt_u32 s12, 0x100
	v_and_b32_e32 v1, 0xf0000, v1
	s_cselect_b64 s[12:13], -1, 0
	v_or3_b32 v1, v8, v1, v2
	s_add_i32 s55, 0, 0x10000
	s_add_i32 s56, 0, 0x14000
	s_ashr_i32 s54, s34, 31
	v_or_b32_e32 v149, s18, v11
	v_mov_b32_e32 v137, v131
	v_add_u32_e32 v138, v1, v9
	v_mov_b32_e32 v138, v241
	v_mov_b32_e32 v139, v131
	v_mov_b64_e32 v[140:141], 0x400
	v_mov_b64_e32 v[142:143], 0x3ff
	v_add_u32_e32 v150, s55, v148
	v_add_u32_e32 v151, s56, v148
	v_add_u32_e32 v152, 0, v0
	v_and_b32_e32 v230, 15, v144
	v_bfe_u32 v231, v144, 4, 2
	v_and_b32_e32 v232, 7, v230
	v_xor_b32_e32 v231, v231, v232
	v_lshlrev_b32_e32 v231, 4, v231
	v_lshl_or_b32 v231, v230, 7, v231
	v_lshrrev_b32_e32 v232, 8, v144
	v_lshl_or_b32 v152, v232, 13, v231
	v_xor_b32_e32 v242, 64, v152
	v_bfe_u32 v232, v144, 6, 2
	v_lshl_or_b32 v150, v232, 12, v231
	v_add_u32_e32 v150, 0x10000, v150
	v_xor_b32_e32 v151, 64, v150
	s_mov_b32 s57, 0x80000
	s_mov_b64 s[14:15], 0x90000
	s_mov_b32 s58, 0x90000
	s_mov_b64 s[18:19], 0xa0000
	s_mov_b32 s59, 0xa0000
	s_mov_b64 s[20:21], 0xb0000
	s_mov_b32 s60, 0xb0000
	s_barrier
	s_branch .LBB0_743

; #define PG8_STAGE(bufoff, gbase, voff) do { _Pragma("unroll") for (int _i = 0; _i < 2; ++_i) \
;         __builtin_amdgcn_global_load_lds((const unsigned*)((const char*)(gbase) + (voff)[_i]), (PG8_LAS unsigned*)(lds + (bufoff) + ldsw + _i * 8192), 16, 0, 0); } while (0)
; #define PG8_LDA(dst, b, h) do { _Pragma("unroll") for (int m = 0; m < 4; ++m) _Pragma("unroll") for (int k = 0; k < 2; ++k) dst[m][k] = *(const PG8_LAS bf16x8*)(lds + PG8_SA(b, h) + aoff + m * 2048 + k * 1024); } while (0)
; #define PG8_LDB(dst, b, h) do { _Pragma("unroll") for (int n = 0; n < 2; ++n) _Pragma("unroll") for (int k = 0; k < 2; ++k) dst[n][k] = *(const PG8_LAS bf16x8*)(lds + PG8_SB(b, h) + boff + n * 2048 + k * 1024); } while (0)
; #define PG8_MMA(ai, bj, At, Bt) do { __builtin_amdgcn_s_setprio(1); _Pragma("unroll") for (int m = 0; m < 4; ++m) _Pragma("unroll") for (int n = 0; n < 2; ++n) _Pragma("unroll") for (int k = 0; k < 2; ++k) \
;         acc[ai][bj][m][n] = __builtin_amdgcn_mfma_f32_16x16x32_bf16(Bt[n][k], At[m][k], acc[ai][bj][m][n], 0, 0, 0); __builtin_amdgcn_s_setprio(0); } while (0)
; #define PG8_WAIT_V(n) asm volatile("s_waitcnt vmcnt(" #n ")" ::: "memory")
; #define PG8_WAIT_L(n) asm volatile("s_waitcnt lgkmcnt(" #n ")" ::: "memory")
; #define PG8_BAR __builtin_amdgcn_s_barrier()
; #define PG8_SCHED __builtin_amdgcn_sched_barrier(0)
; template <class Epi, class Sched, bool ALIGN_EPI = false, bool SP2 = false>
; __device__ __forceinline__ void gemm_phase(PG8_LAS unsigned char* lds, const Gemm g, const Sched& S, const Epi& E) {
;     ...
;             PG8_LDB(B0, 0, 0); PG8_LDB(B1, 0, 1); PG8_SCHED; PG8_LDA(At, 0, 0); PG8_STAGE(PG8_SA(1, 1), a1 + hstep, voffA);
;             PG8_WAIT_V(8); PG8_WAIT_L(0); PG8_BAR; PG8_MMA(0, 0, At, B0); PG8_MMA(0, 1, At, B1); PG8_BAR; PG8_SCHED;
;             PG8_LDA(At, 0, 1); PG8_STAGE(PG8_SB(0, 0), b2, voffB); PG8_STAGE(PG8_SB(0, 1), b2 + hstep, voffB); PG8_STAGE(PG8_SA(0, 0), a2, voffA);
;             PG8_WAIT_V(8); PG8_WAIT_L(0); PG8_BAR; PG8_MMA(1, 0, At, B0); PG8_MMA(1, 1, At, B1); PG8_BAR; PG8_SCHED;
.LBB0_750:
	ds_read_b128 v[154:157], v150
	ds_read_b128 v[160:163], v151
	ds_read_b128 v[164:167], v150 offset:2048
	ds_read_b128 v[168:171], v151 offset:2048
	ds_read_b128 v[172:175], v150 offset:16384
	ds_read_b128 v[176:179], v151 offset:16384
	ds_read_b128 v[180:183], v150 offset:18432
	ds_read_b128 v[184:187], v151 offset:18432
	s_add_u32 s36, s38, 0xfff80080
	s_addc_u32 s37, s39, -1
	s_cmp_eq_u32 s66, 28
	s_cselect_b32 s43, s25, s37
	s_cselect_b32 s42, s62, s36
	s_cselect_b32 s41, s23, s65
	s_cselect_b32 s40, s63, s64
	v_lshl_add_u64 v[146:147], s[38:39], 0, v[136:137]
	s_add_i32 m0, s31, 0xc000
	ds_read_b128 v[188:191], v152
	ds_read_b128 v[192:195], v242
	ds_read_b128 v[196:199], v152 offset:2048
	ds_read_b128 v[200:203], v242 offset:2048
	ds_read_b128 v[204:207], v152 offset:4096
	ds_read_b128 v[208:211], v242 offset:4096
	ds_read_b128 v[212:215], v152 offset:6144
	ds_read_b128 v[216:219], v242 offset:6144
	global_load_lds_dwordx4 v[146:147], off
	v_lshl_add_u64 v[146:147], s[38:39], 0, v[138:139]
	s_add_i32 m0, s31, 0xe000
	s_nop 0
	global_load_lds_dwordx4 v[146:147], off
	s_waitcnt vmcnt(8)
	s_waitcnt lgkmcnt(0)
	s_barrier
	s_setprio 1
	s_waitcnt lgkmcnt(0)
	v_mfma_f32_16x16x32_bf16 v[124:127], v[154:157], v[188:191], v[124:127]
	v_mfma_f32_16x16x32_bf16 v[120:123], v[164:167], v[188:191], v[120:123]
	v_mfma_f32_16x16x32_bf16 v[116:119], v[154:157], v[196:199], v[116:119]
	v_mfma_f32_16x16x32_bf16 v[108:111], v[164:167], v[196:199], v[108:111]
	v_mfma_f32_16x16x32_bf16 v[100:103], v[154:157], v[204:207], v[100:103]
	v_mfma_f32_16x16x32_bf16 v[92:95], v[164:167], v[204:207], v[92:95]
	v_mfma_f32_16x16x32_bf16 v[84:87], v[154:157], v[212:215], v[84:87]
	v_mfma_f32_16x16x32_bf16 v[76:79], v[164:167], v[212:215], v[76:79]
	v_mfma_f32_16x16x32_bf16 v[124:127], v[160:163], v[192:195], v[124:127]
	v_mfma_f32_16x16x32_bf16 v[120:123], v[168:171], v[192:195], v[120:123]
	v_mfma_f32_16x16x32_bf16 v[116:119], v[160:163], v[200:203], v[116:119]
	v_mfma_f32_16x16x32_bf16 v[108:111], v[168:171], v[200:203], v[108:111]
	v_mfma_f32_16x16x32_bf16 v[100:103], v[160:163], v[208:211], v[100:103]
	v_mfma_f32_16x16x32_bf16 v[92:95], v[168:171], v[208:211], v[92:95]
	v_mfma_f32_16x16x32_bf16 v[84:87], v[160:163], v[216:219], v[84:87]
	v_mfma_f32_16x16x32_bf16 v[76:79], v[168:171], v[216:219], v[76:79]
	s_setprio 0
	s_setprio 1
	v_mfma_f32_16x16x32_bf16 v[112:115], v[172:175], v[188:191], v[112:115]
	v_mfma_f32_16x16x32_bf16 v[104:107], v[180:183], v[188:191], v[104:107]
	v_mfma_f32_16x16x32_bf16 v[96:99], v[172:175], v[196:199], v[96:99]
	v_mfma_f32_16x16x32_bf16 v[88:91], v[180:183], v[196:199], v[88:91]
	v_mfma_f32_16x16x32_bf16 v[80:83], v[172:175], v[204:207], v[80:83]
	v_mfma_f32_16x16x32_bf16 v[72:75], v[180:183], v[204:207], v[72:75]
	v_mfma_f32_16x16x32_bf16 v[68:71], v[172:175], v[212:215], v[68:71]
	v_mfma_f32_16x16x32_bf16 v[64:67], v[180:183], v[212:215], v[64:67]
	v_mfma_f32_16x16x32_bf16 v[112:115], v[176:179], v[192:195], v[112:115]
	v_mfma_f32_16x16x32_bf16 v[104:107], v[184:187], v[192:195], v[104:107]
	v_mfma_f32_16x16x32_bf16 v[96:99], v[176:179], v[200:203], v[96:99]
	v_mfma_f32_16x16x32_bf16 v[88:91], v[184:187], v[200:203], v[88:91]
	v_mfma_f32_16x16x32_bf16 v[80:83], v[176:179], v[208:211], v[80:83]
	v_mfma_f32_16x16x32_bf16 v[72:75], v[184:187], v[208:211], v[72:75]
	v_mfma_f32_16x16x32_bf16 v[68:71], v[176:179], v[216:219], v[68:71]
	v_mfma_f32_16x16x32_bf16 v[64:67], v[184:187], v[216:219], v[64:67]
	s_setprio 0
	s_barrier
	s_add_i32 s36, s55, s47
	v_lshl_add_u64 v[146:147], s[40:41], 0, v[130:131]
	s_mov_b32 m0, s36
	ds_read_b128 v[188:191], v152 offset:16384
	ds_read_b128 v[192:195], v242 offset:16384
	ds_read_b128 v[196:199], v152 offset:18432
	ds_read_b128 v[200:203], v242 offset:18432
	ds_read_b128 v[204:207], v152 offset:20480
	ds_read_b128 v[208:211], v242 offset:20480
	ds_read_b128 v[212:215], v152 offset:22528
	ds_read_b128 v[216:219], v242 offset:22528
	global_load_lds_dwordx4 v[146:147], off
	s_add_i32 m0, s36, 0x2000
	s_add_u32 s36, s40, 0x80000
	v_lshl_add_u64 v[220:221], s[40:41], 0, v[134:135]
	s_addc_u32 s37, s41, 0
	s_add_i32 s67, s56, s47
	global_load_lds_dwordx4 v[220:221], off
	v_lshl_add_u64 v[222:223], s[36:37], 0, v[130:131]
	s_mov_b32 m0, s67
	v_lshl_add_u64 v[224:225], s[42:43], 0, v[132:133]
	global_load_lds_dwordx4 v[222:223], off
	v_lshl_add_u64 v[222:223], s[36:37], 0, v[134:135]
	s_add_i32 m0, s67, 0x2000
	s_nop 0
	global_load_lds_dwordx4 v[222:223], off
	v_lshl_add_u64 v[222:223], s[42:43], 0, v[128:129]
	s_mov_b32 m0, s31
	s_nop 0
	global_load_lds_dwordx4 v[222:223], off
	s_mov_b32 m0, s48
	s_nop 0
	global_load_lds_dwordx4 v[224:225], off
	s_waitcnt vmcnt(8)
	s_waitcnt lgkmcnt(0)
	s_barrier
; #define PG8_STAGE(bufoff, gbase, voff) do { _Pragma("unroll") for (int _i = 0; _i < 2; ++_i) \
;         __builtin_amdgcn_global_load_lds((const unsigned*)((const char*)(gbase) + (voff)[_i]), (PG8_LAS unsigned*)(lds + (bufoff) + ldsw + _i * 8192), 16, 0, 0); } while (0)
; #define PG8_LDA(dst, b, h) do { _Pragma("unroll") for (int m = 0; m < 4; ++m) _Pragma("unroll") for (int k = 0; k < 2; ++k) dst[m][k] = *(const PG8_LAS bf16x8*)(lds + PG8_SA(b, h) + aoff + m * 2048 + k * 1024); } while (0)
; #define PG8_LDB(dst, b, h) do { _Pragma("unroll") for (int n = 0; n < 2; ++n) _Pragma("unroll") for (int k = 0; k < 2; ++k) dst[n][k] = *(const PG8_LAS bf16x8*)(lds + PG8_SB(b, h) + boff + n * 2048 + k * 1024); } while (0)
; #define PG8_MMA(ai, bj, At, Bt) do { __builtin_amdgcn_s_setprio(1); _Pragma("unroll") for (int m = 0; m < 4; ++m) _Pragma("unroll") for (int n = 0; n < 2; ++n) _Pragma("unroll") for (int k = 0; k < 2; ++k) \
;         acc[ai][bj][m][n] = __builtin_amdgcn_mfma_f32_16x16x32_bf16(Bt[n][k], At[m][k], acc[ai][bj][m][n], 0, 0, 0); __builtin_amdgcn_s_setprio(0); } while (0)
; #define PG8_WAIT_V(n) asm volatile("s_waitcnt vmcnt(" #n ")" ::: "memory")
; #define PG8_WAIT_L(n) asm volatile("s_waitcnt lgkmcnt(" #n ")" ::: "memory")
; #define PG8_BAR __builtin_amdgcn_s_barrier()
; #define PG8_SCHED __builtin_amdgcn_sched_barrier(0)
; template <class Epi, class Sched, bool ALIGN_EPI = false, bool SP2 = false>
; __device__ __forceinline__ void gemm_phase(PG8_LAS unsigned char* lds, const Gemm g, const Sched& S, const Epi& E) {
;     ...
;             PG8_WAIT_V(8); PG8_WAIT_L(0); PG8_BAR; PG8_MMA(1, 0, At, B0); PG8_MMA(1, 1, At, B1); PG8_BAR; PG8_SCHED;
;             PG8_LDB(B0, 1, 0); PG8_LDB(B1, 1, 1); PG8_SCHED; PG8_LDA(At, 1, 0); PG8_STAGE(PG8_SA(0, 1), a2 + hstep, voffA);
;             PG8_WAIT_V(8); PG8_WAIT_L(0); PG8_BAR; PG8_MMA(0, 0, At, B0); PG8_MMA(0, 1, At, B1); PG8_BAR; PG8_SCHED;
	s_setprio 1
	s_waitcnt lgkmcnt(0)
	v_mfma_f32_16x16x32_bf16 v[60:63], v[154:157], v[188:191], v[60:63]
	v_mfma_f32_16x16x32_bf16 v[56:59], v[164:167], v[188:191], v[56:59]
	v_mfma_f32_16x16x32_bf16 v[52:55], v[154:157], v[196:199], v[52:55]
	v_mfma_f32_16x16x32_bf16 v[44:47], v[164:167], v[196:199], v[44:47]
	v_mfma_f32_16x16x32_bf16 v[36:39], v[154:157], v[204:207], v[36:39]
	v_mfma_f32_16x16x32_bf16 v[28:31], v[164:167], v[204:207], v[28:31]
	v_mfma_f32_16x16x32_bf16 v[20:23], v[154:157], v[212:215], v[20:23]
	v_mfma_f32_16x16x32_bf16 v[12:15], v[164:167], v[212:215], v[12:15]
	v_mfma_f32_16x16x32_bf16 v[60:63], v[160:163], v[192:195], v[60:63]
	v_mfma_f32_16x16x32_bf16 v[56:59], v[168:171], v[192:195], v[56:59]
	v_mfma_f32_16x16x32_bf16 v[52:55], v[160:163], v[200:203], v[52:55]
	v_mfma_f32_16x16x32_bf16 v[44:47], v[168:171], v[200:203], v[44:47]
	v_mfma_f32_16x16x32_bf16 v[36:39], v[160:163], v[208:211], v[36:39]
	v_mfma_f32_16x16x32_bf16 v[28:31], v[168:171], v[208:211], v[28:31]
	v_mfma_f32_16x16x32_bf16 v[20:23], v[160:163], v[216:219], v[20:23]
	v_mfma_f32_16x16x32_bf16 v[12:15], v[168:171], v[216:219], v[12:15]
	s_setprio 0
	s_setprio 1
	v_mfma_f32_16x16x32_bf16 v[48:51], v[172:175], v[188:191], v[48:51]
	v_mfma_f32_16x16x32_bf16 v[40:43], v[180:183], v[188:191], v[40:43]
	v_mfma_f32_16x16x32_bf16 v[32:35], v[172:175], v[196:199], v[32:35]
	v_mfma_f32_16x16x32_bf16 v[24:27], v[180:183], v[196:199], v[24:27]
	v_mfma_f32_16x16x32_bf16 v[16:19], v[172:175], v[204:207], v[16:19]
	v_mfma_f32_16x16x32_bf16 v[8:11], v[180:183], v[204:207], v[8:11]
	v_mfma_f32_16x16x32_bf16 v[4:7], v[172:175], v[212:215], v[4:7]
	v_mfma_f32_16x16x32_bf16 v[0:3], v[180:183], v[212:215], v[0:3]
	v_mfma_f32_16x16x32_bf16 v[48:51], v[176:179], v[192:195], v[48:51]
	v_mfma_f32_16x16x32_bf16 v[40:43], v[184:187], v[192:195], v[40:43]
	v_mfma_f32_16x16x32_bf16 v[32:35], v[176:179], v[200:203], v[32:35]
	v_mfma_f32_16x16x32_bf16 v[24:27], v[184:187], v[200:203], v[24:27]
	v_mfma_f32_16x16x32_bf16 v[16:19], v[176:179], v[208:211], v[16:19]
	v_mfma_f32_16x16x32_bf16 v[8:11], v[184:187], v[208:211], v[8:11]
	v_mfma_f32_16x16x32_bf16 v[4:7], v[176:179], v[216:219], v[4:7]
	v_mfma_f32_16x16x32_bf16 v[0:3], v[184:187], v[216:219], v[0:3]
	s_setprio 0
	s_barrier
	s_add_i32 s67, 0, 0x18000
	v_add_u32_e32 v153, s67, v148
	s_add_i32 s68, 0, 0x1c000
	ds_read_b128 v[154:157], v150 offset:32768
	ds_read_b128 v[160:163], v151 offset:32768
	ds_read_b128 v[164:167], v150 offset:34816
	ds_read_b128 v[168:171], v151 offset:34816
	v_add_u32_e32 v153, s68, v148
	ds_read_b128 v[172:175], v150 offset:49152
	ds_read_b128 v[176:179], v151 offset:49152
	ds_read_b128 v[180:183], v150 offset:51200
	ds_read_b128 v[184:187], v151 offset:51200
	s_add_u32 s36, s42, 0x80000
	s_addc_u32 s37, s43, 0
	s_mov_b32 m0, s49
	v_lshl_add_u64 v[226:227], s[36:37], 0, v[128:129]
	ds_read_b128 v[188:191], v152 offset:32768
	ds_read_b128 v[192:195], v242 offset:32768
	ds_read_b128 v[196:199], v152 offset:34816
	ds_read_b128 v[200:203], v242 offset:34816
	ds_read_b128 v[204:207], v152 offset:36864
	ds_read_b128 v[208:211], v242 offset:36864
	ds_read_b128 v[212:215], v152 offset:38912
	ds_read_b128 v[216:219], v242 offset:38912
	global_load_lds_dwordx4 v[226:227], off
	v_lshl_add_u64 v[226:227], s[36:37], 0, v[132:133]
	s_mov_b32 m0, s50
	s_nop 0
	global_load_lds_dwordx4 v[226:227], off
	s_waitcnt vmcnt(8)
	s_waitcnt lgkmcnt(0)
	s_barrier
	s_setprio 1
	s_waitcnt lgkmcnt(0)
	v_mfma_f32_16x16x32_bf16 v[124:127], v[154:157], v[188:191], v[124:127]
	v_mfma_f32_16x16x32_bf16 v[120:123], v[164:167], v[188:191], v[120:123]
	v_mfma_f32_16x16x32_bf16 v[116:119], v[154:157], v[196:199], v[116:119]
	v_mfma_f32_16x16x32_bf16 v[108:111], v[164:167], v[196:199], v[108:111]
	v_mfma_f32_16x16x32_bf16 v[100:103], v[154:157], v[204:207], v[100:103]
	v_mfma_f32_16x16x32_bf16 v[92:95], v[164:167], v[204:207], v[92:95]
	v_mfma_f32_16x16x32_bf16 v[84:87], v[154:157], v[212:215], v[84:87]
	v_mfma_f32_16x16x32_bf16 v[76:79], v[164:167], v[212:215], v[76:79]
	v_mfma_f32_16x16x32_bf16 v[124:127], v[160:163], v[192:195], v[124:127]
	v_mfma_f32_16x16x32_bf16 v[120:123], v[168:171], v[192:195], v[120:123]
	v_mfma_f32_16x16x32_bf16 v[116:119], v[160:163], v[200:203], v[116:119]
	v_mfma_f32_16x16x32_bf16 v[108:111], v[168:171], v[200:203], v[108:111]
	v_mfma_f32_16x16x32_bf16 v[100:103], v[160:163], v[208:211], v[100:103]
	v_mfma_f32_16x16x32_bf16 v[92:95], v[168:171], v[208:211], v[92:95]
	v_mfma_f32_16x16x32_bf16 v[84:87], v[160:163], v[216:219], v[84:87]
	v_mfma_f32_16x16x32_bf16 v[76:79], v[168:171], v[216:219], v[76:79]
	s_setprio 0
	s_setprio 1
	v_mfma_f32_16x16x32_bf16 v[112:115], v[172:175], v[188:191], v[112:115]
	v_mfma_f32_16x16x32_bf16 v[104:107], v[180:183], v[188:191], v[104:107]
	v_mfma_f32_16x16x32_bf16 v[96:99], v[172:175], v[196:199], v[96:99]
	v_mfma_f32_16x16x32_bf16 v[88:91], v[180:183], v[196:199], v[88:91]
	v_mfma_f32_16x16x32_bf16 v[80:83], v[172:175], v[204:207], v[80:83]
	v_mfma_f32_16x16x32_bf16 v[72:75], v[180:183], v[204:207], v[72:75]
	v_mfma_f32_16x16x32_bf16 v[68:71], v[172:175], v[212:215], v[68:71]
	v_mfma_f32_16x16x32_bf16 v[64:67], v[180:183], v[212:215], v[64:67]
	v_mfma_f32_16x16x32_bf16 v[112:115], v[176:179], v[192:195], v[112:115]
	v_mfma_f32_16x16x32_bf16 v[104:107], v[184:187], v[192:195], v[104:107]
	v_mfma_f32_16x16x32_bf16 v[96:99], v[176:179], v[200:203], v[96:99]
	v_mfma_f32_16x16x32_bf16 v[88:91], v[184:187], v[200:203], v[88:91]
	v_mfma_f32_16x16x32_bf16 v[80:83], v[176:179], v[208:211], v[80:83]
	v_mfma_f32_16x16x32_bf16 v[72:75], v[184:187], v[208:211], v[72:75]
	v_mfma_f32_16x16x32_bf16 v[68:71], v[176:179], v[216:219], v[68:71]
	v_mfma_f32_16x16x32_bf16 v[64:67], v[184:187], v[216:219], v[64:67]
	s_setprio 0
	s_barrier
; #define PG8_STAGE(bufoff, gbase, voff) do { _Pragma("unroll") for (int _i = 0; _i < 2; ++_i) \
;         __builtin_amdgcn_global_load_lds((const unsigned*)((const char*)(gbase) + (voff)[_i]), (PG8_LAS unsigned*)(lds + (bufoff) + ldsw + _i * 8192), 16, 0, 0); } while (0)
; #define PG8_LDA(dst, b, h) do { _Pragma("unroll") for (int m = 0; m < 4; ++m) _Pragma("unroll") for (int k = 0; k < 2; ++k) dst[m][k] = *(const PG8_LAS bf16x8*)(lds + PG8_SA(b, h) + aoff + m * 2048 + k * 1024); } while (0)
; #define PG8_MMA(ai, bj, At, Bt) do { __builtin_amdgcn_s_setprio(1); _Pragma("unroll") for (int m = 0; m < 4; ++m) _Pragma("unroll") for (int n = 0; n < 2; ++n) _Pragma("unroll") for (int k = 0; k < 2; ++k) \
;         acc[ai][bj][m][n] = __builtin_amdgcn_mfma_f32_16x16x32_bf16(Bt[n][k], At[m][k], acc[ai][bj][m][n], 0, 0, 0); __builtin_amdgcn_s_setprio(0); } while (0)
; #define PG8_WAIT_V(n) asm volatile("s_waitcnt vmcnt(" #n ")" ::: "memory")
; #define PG8_WAIT_L(n) asm volatile("s_waitcnt lgkmcnt(" #n ")" ::: "memory")
; #define PG8_BAR __builtin_amdgcn_s_barrier()
; #define PG8_SCHED __builtin_amdgcn_sched_barrier(0)
; template <class Epi, class Sched, bool ALIGN_EPI = false, bool SP2 = false>
; __device__ __forceinline__ void gemm_phase(PG8_LAS unsigned char* lds, const Gemm g, const Sched& S, const Epi& E) {
;     ...
;         for (int t = 0; t < nt; t += 2) {
;             const bool last = (t == nt - 2);
;     ...
;             PG8_LDA(At, 1, 1); PG8_STAGE(PG8_SB(1, 0), b3, voffB); PG8_STAGE(PG8_SB(1, 1), b3 + hstep, voffB); PG8_STAGE(PG8_SA(1, 0), a3, voffA);
;             PG8_WAIT_V(8); PG8_WAIT_L(0); PG8_BAR; PG8_MMA(1, 0, At, B0); PG8_MMA(1, 1, At, B1); PG8_BAR; PG8_SCHED;
	s_add_i32 s36, s67, s47
	v_lshl_add_u64 v[146:147], v[146:147], 0, s[10:11]
	s_mov_b32 m0, s36
	ds_read_b128 v[188:191], v152 offset:49152
	ds_read_b128 v[192:195], v242 offset:49152
	ds_read_b128 v[196:199], v152 offset:51200
	ds_read_b128 v[200:203], v242 offset:51200
	ds_read_b128 v[204:207], v152 offset:53248
	ds_read_b128 v[208:211], v242 offset:53248
	ds_read_b128 v[212:215], v152 offset:55296
	ds_read_b128 v[216:219], v242 offset:55296
	global_load_lds_dwordx4 v[146:147], off
	s_add_i32 m0, s36, 0x2000
	s_add_u32 s36, s40, 0x80080
	v_lshl_add_u64 v[146:147], v[220:221], 0, s[10:11]
	s_addc_u32 s37, s41, 0
	s_add_i32 s40, s68, s47
	global_load_lds_dwordx4 v[146:147], off
	v_lshl_add_u64 v[146:147], s[36:37], 0, v[130:131]
	s_mov_b32 m0, s40
	s_nop 0
	global_load_lds_dwordx4 v[146:147], off
	v_lshl_add_u64 v[146:147], s[36:37], 0, v[134:135]
	s_add_i32 m0, s40, 0x2000
	s_nop 0
	global_load_lds_dwordx4 v[146:147], off
	v_lshl_add_u64 v[146:147], v[222:223], 0, s[10:11]
	s_mov_b32 m0, s52
	s_nop 0
	global_load_lds_dwordx4 v[146:147], off
	v_lshl_add_u64 v[146:147], v[224:225], 0, s[10:11]
	s_mov_b32 m0, s53
	s_nop 0
	global_load_lds_dwordx4 v[146:147], off
	s_waitcnt vmcnt(8)
	s_waitcnt lgkmcnt(0)
	s_barrier
	s_setprio 1
	s_waitcnt lgkmcnt(0)
	v_mfma_f32_16x16x32_bf16 v[60:63], v[154:157], v[188:191], v[60:63]
	v_mfma_f32_16x16x32_bf16 v[56:59], v[164:167], v[188:191], v[56:59]
	v_mfma_f32_16x16x32_bf16 v[52:55], v[154:157], v[196:199], v[52:55]
	v_mfma_f32_16x16x32_bf16 v[44:47], v[164:167], v[196:199], v[44:47]
	v_mfma_f32_16x16x32_bf16 v[36:39], v[154:157], v[204:207], v[36:39]
	v_mfma_f32_16x16x32_bf16 v[28:31], v[164:167], v[204:207], v[28:31]
	v_mfma_f32_16x16x32_bf16 v[20:23], v[154:157], v[212:215], v[20:23]
	v_mfma_f32_16x16x32_bf16 v[12:15], v[164:167], v[212:215], v[12:15]
	v_mfma_f32_16x16x32_bf16 v[60:63], v[160:163], v[192:195], v[60:63]
	v_mfma_f32_16x16x32_bf16 v[56:59], v[168:171], v[192:195], v[56:59]
	v_mfma_f32_16x16x32_bf16 v[52:55], v[160:163], v[200:203], v[52:55]
	v_mfma_f32_16x16x32_bf16 v[44:47], v[168:171], v[200:203], v[44:47]
	v_mfma_f32_16x16x32_bf16 v[36:39], v[160:163], v[208:211], v[36:39]
	v_mfma_f32_16x16x32_bf16 v[28:31], v[168:171], v[208:211], v[28:31]
	v_mfma_f32_16x16x32_bf16 v[20:23], v[160:163], v[216:219], v[20:23]
	v_mfma_f32_16x16x32_bf16 v[12:15], v[168:171], v[216:219], v[12:15]
	s_setprio 0
	s_setprio 1
	v_mfma_f32_16x16x32_bf16 v[48:51], v[172:175], v[188:191], v[48:51]
	v_mfma_f32_16x16x32_bf16 v[40:43], v[180:183], v[188:191], v[40:43]
	v_mfma_f32_16x16x32_bf16 v[32:35], v[172:175], v[196:199], v[32:35]
	v_mfma_f32_16x16x32_bf16 v[24:27], v[180:183], v[196:199], v[24:27]
	v_mfma_f32_16x16x32_bf16 v[16:19], v[172:175], v[204:207], v[16:19]
	v_mfma_f32_16x16x32_bf16 v[8:11], v[180:183], v[204:207], v[8:11]
	v_mfma_f32_16x16x32_bf16 v[4:7], v[172:175], v[212:215], v[4:7]
	v_mfma_f32_16x16x32_bf16 v[0:3], v[180:183], v[212:215], v[0:3]
	v_mfma_f32_16x16x32_bf16 v[48:51], v[176:179], v[192:195], v[48:51]
	v_mfma_f32_16x16x32_bf16 v[40:43], v[184:187], v[192:195], v[40:43]
	v_mfma_f32_16x16x32_bf16 v[32:35], v[176:179], v[200:203], v[32:35]
	v_mfma_f32_16x16x32_bf16 v[24:27], v[184:187], v[200:203], v[24:27]
	v_mfma_f32_16x16x32_bf16 v[16:19], v[176:179], v[208:211], v[16:19]
	v_mfma_f32_16x16x32_bf16 v[8:11], v[184:187], v[208:211], v[8:11]
	v_mfma_f32_16x16x32_bf16 v[4:7], v[176:179], v[216:219], v[4:7]
	v_mfma_f32_16x16x32_bf16 v[0:3], v[184:187], v[216:219], v[0:3]
	s_setprio 0
	s_barrier
	s_add_i32 s66, s66, 2
	s_add_u32 s38, s38, 0x100
	s_addc_u32 s39, s39, 0
	s_add_u32 s64, s64, 0x100
	s_addc_u32 s65, s65, 0
	s_cmp_gt_u32 s66, 29
	s_cbranch_scc0 .LBB0_750
	s_and_b64 vcc, exec, s[12:13]
	s_cbranch_vccz .LBB0_753
	s_barrier

; template <class Epi, class Sched, bool ALIGN_EPI = false, bool SP2 = false>
; __device__ __forceinline__ void gemm_phase(PG8_LAS unsigned char* lds, const Gemm g, const Sched& S, const Epi& E) {
;     ...
;     for (int i = 0; i < 2; ++i) { int R, C; stage_rc(tid * 16 + i * 8192, R, C); const int Rb = Epi::PERM ? ((R & ~31) + perm32(R & 31)) : R;
;         voffA[i] = (unsigned)(R * K + C) * 2u; voffB[i] = (unsigned)(Rb * K + C) * 2u; }
; __global__ void __launch_bounds__(NTHREADS, 2) fwd_kernel(Params p) {
;     ...
;     if (RUN(11)) {
;         pg8::Gemm g{(const bf16_t*)(ws + WS_ACT), (const bf16_t*)(ws + WS_WDN), T, DM, DFF}; pg8::StaticOrder S; S.init(T, DM, G, cid);
;         EpiPlainBf16 E{(bf16_t*)(ws + WS_BR2), DM};
;         pg8::gemm_phase<EpiPlainBf16, pg8::StaticOrder, true, true>(ring, g, S, E);
.LBB0_1038:
	v_readlane_b32 s4, v246, 12
	v_readlane_b32 s5, v246, 13
	s_cmp_lt_i32 s4, 12
	s_cselect_b64 s[4:5], -1, 0
	s_and_b64 s[0:1], s[4:5], s[0:1]
	s_andn2_b64 vcc, exec, s[0:1]
	v_readlane_b32 s6, v246, 14
	v_readlane_b32 s7, v246, 15
	s_cbranch_vccnz .LBB0_1067
	v_lshrrev_b32_e32 v238, 3, v144
	v_and_b32_e32 v239, 7, v144
	v_and_b32_e32 v240, 7, v238
	v_xor_b32_e32 v239, v239, v240
	v_lshlrev_b32_e32 v239, 4, v239
	v_mul_u32_u24_e32 v240, 0x2b00, v238
	v_add_u32_e32 v240, v240, v239
	v_add_u32_e32 v241, 0xac000, v240
	v_and_b32_e32 v242, 31, v238
	v_bfe_u32 v243, v242, 2, 2
	v_lshlrev_b32_e32 v243, 3, v243
	v_lshrrev_b32_e32 v230, 4, v242
	v_lshl_or_b32 v243, v230, 2, v243
	v_and_b32_e32 v230, 3, v242
	v_or_b32_e32 v243, v243, v230
	v_and_b32_e32 v230, 32, v238
	v_or_b32_e32 v243, v243, v230
	v_mul_u32_u24_e32 v238, 0x2b00, v243
	v_add_u32_e32 v238, v238, v239
	v_add_u32_e32 v239, 0xac000, v238
	v_readlane_b32 s0, v246, 0
	s_cmpk_gt_i32 s0, 0x3ff
	v_readfirstlane_b32 s2, v144
	v_readlane_b32 s1, v246, 1
	s_cbranch_scc1 .LBB0_1067
	v_readlane_b32 s0, v246, 0
	s_ashr_i32 s30, s0, 31
	s_mov_b32 s8, s0
	s_lshr_b32 s0, s30, 29
	s_add_i32 s6, s8, s0
	s_and_b32 s0, s6, -8
	s_sub_i32 s7, s8, s0
	s_cmp_gt_i32 s7, -1
	v_readlane_b32 s1, v246, 1
	s_cbranch_scc0 .LBB0_1042
	s_lshl_b32 s3, s7, 7
	s_ashr_i32 s6, s6, 3
	s_cbranch_execz .LBB0_1043
	s_branch .LBB0_1044

; #define PG8_STAGE(bufoff, gbase, voff) do { _Pragma("unroll") for (int _i = 0; _i < 2; ++_i) \
;         __builtin_amdgcn_global_load_lds((const unsigned*)((const char*)(gbase) + (voff)[_i]), (PG8_LAS unsigned*)(lds + (bufoff) + ldsw + _i * 8192), 16, 0, 0); } while (0)
; #define PG8_WAIT_V(n) asm volatile("s_waitcnt vmcnt(" #n ")" ::: "memory")
; #define PG8_BAR __builtin_amdgcn_s_barrier()
;     __device__ bool next(int i, pg8::Unit& u) const { if (!base.next(i >> 1, u)) return false; u.seg = i & 1; return true; }
; template <class Epi, class Sched, bool ALIGN_EPI = false, bool SP2 = false>
; __device__ __forceinline__ void gemm_phase(PG8_LAS unsigned char* lds, const Gemm g, const Sched& S, const Epi& E) {
;     ...
;     for (int i = 0; i < 2; ++i) { int R, C; stage_rc(tid * 16 + i * 8192, R, C); const int Rb = Epi::PERM ? ((R & ~31) + perm32(R & 31)) : R;
;         voffA[i] = (unsigned)(R * K + C) * 2u; voffB[i] = (unsigned)(Rb * K + C) * 2u; }
;     const size_t kstep = (size_t)(BK * 2);
;     const size_t hstep = (size_t)HALF * K * 2;
;     const size_t tstep = 2 * hstep;
;     const unsigned ldsw = (unsigned)wid * 1024u;
;     const int aoff = lds_byte(wr * 64 + fr, fq * 8), boff = lds_byte(wc * 32 + fr, fq * 8);
;     ...
;     Unit cur, nxt; int ui = 0;
;     if (!S.next(0, cur)) return;
;     f32x4 acc[2][2][4][2];
; #pragma unroll
;     for (int a = 0; a < 2; ++a)
; #pragma unroll
;         for (int b = 0; b < 2; ++b)
; #pragma unroll
;             for (int m = 0; m < 4; ++m)
; #pragma unroll
;                 for (int n = 0; n < 2; ++n) acc[a][b][m][n] = (f32x4){0.f, 0.f, 0.f, 0.f};
;     bf16x8 At[4][2], B0[2][2], B1[2][2];
;     const char* cA = (const char*)(cur.seg ? g.A2 : g.A) + (size_t)cur.pm * tstep; const char* cB = (const char*)(cur.seg ? g.Bt2 : g.Bt) + (size_t)cur.pn * tstep;
;     S.a_ready(cur);
;     if constexpr (SP2) {
;         PG8_STAGE(PG8_SB(0, 0), cB, voffB); PG8_STAGE(PG8_SB(0, 1), cB + hstep, voffB); PG8_STAGE(PG8_SA(0, 0), cA, voffA); PG8_STAGE(PG8_SA(0, 1), cA + hstep, voffA);
;         if (wr == 1) PG8_BAR;
;         PG8_WAIT_V(2); PG8_BAR;
;         PG8_STAGE(PG8_SB(1, 0), cB + kstep, voffB); PG8_STAGE(PG8_SA(1, 0), cA + kstep, voffA); PG8_STAGE(PG8_SB(1, 1), cB + hstep + kstep, voffB);
;         PG8_WAIT_V(6); PG8_BAR;
.LBB0_1044:
	v_readlane_b32 s0, v246, 10
	v_readlane_b32 s1, v246, 11
	s_add_u32 s31, s0, 0x26000000
	s_addc_u32 s33, s1, 0
	s_add_u32 s35, s0, 0x6900000
	s_addc_u32 s38, s1, 0
	s_add_i32 s3, s3, s6
	s_ashr_i32 s6, s3, 31
	s_lshr_b32 s6, s6, 26
	s_add_i32 s6, s3, s6
	s_ashr_i32 s7, s6, 6
	s_and_b32 s6, s6, 0xffc0
	s_sub_i32 s6, s3, s6
	s_waitcnt vmcnt(0)
	v_lshrrev_b32_e32 v3, 1, v144
	s_bfe_i32 s3, s6, 0x80000
	v_and_b32_e32 v10, 24, v3
	v_lshrrev_b32_e32 v3, 5, v144
	s_bfe_u32 s3, s3, 0x3000c
	v_and_b32_e32 v3, 4, v3
	v_bfe_u32 v4, v144, 2, 2
	s_add_i32 s8, s6, s3
	v_lshlrev_b32_e32 v0, 4, v144
	v_and_b32_e32 v1, 32, v144
	s_waitcnt lgkmcnt(0)
	v_bfe_u32 v2, v144, 2, 4
	v_or3_b32 v3, v3, v4, v10
	v_lshrrev_b32_e32 v4, 3, v144
	s_movk_i32 s0, 0x70
	s_bfe_i32 s3, s8, 0x80000
	s_and_b32 s8, s8, 0xf8
	v_bitop3_b32 v8, v0, v1, 48 bitop3:0x6c
	v_and_or_b32 v5, v4, s0, v2
	s_movk_i32 s0, 0x60
	v_add_u32_e32 v0, 0x2000, v0
	s_sub_i32 s6, s6, s8
	v_and_or_b32 v4, v4, s0, v3
	v_lshrrev_b32_e32 v0, 7, v0
	s_movk_i32 s0, 0xf0
	s_lshl_b32 s7, s7, 3
	s_sext_i32_i16 s9, s3
	s_sext_i32_i8 s6, s6
	s_lshr_b32 s1, s2, 6
	v_and_b32_e32 v9, 64, v144
	v_and_or_b32 v2, v0, s0, v2
	s_movk_i32 s0, 0xe0
	s_add_i32 s56, s7, s6
	s_ashr_i32 s6, s9, 3
	v_or_b32_e32 v1, v8, v9
	v_and_or_b32 v0, v0, s0, v3
	s_lshr_b32 s0, s2, 8
	s_lshl_b32 s39, s1, 10
	s_lshr_b32 s3, s9, 3
	s_mul_hi_i32 s7, s6, 0x2b0000
	s_mul_i32 s6, s6, 0x2b0000
	v_lshrrev_b32_e32 v1, 1, v1
	v_mul_u32_u24_e32 v4, 0x1580, v4
	s_add_u32 s26, s35, s6
	v_or_b32_e32 v4, v4, v1
	s_addc_u32 s27, s38, s7
	s_add_i32 s40, s39, 0
	v_lshlrev_b32_e32 v130, 1, v4
	v_mov_b32_e32 v130, v238
	v_mul_u32_u24_e32 v0, 0x1580, v0
	s_add_i32 m0, s40, 0x10000
	v_or_b32_e32 v0, v0, v1
	global_load_lds_dwordx4 v130, s[26:27]
	s_add_i32 m0, s40, 0x12000
	v_lshlrev_b32_e32 v134, 1, v0
	v_mov_b32_e32 v134, v239
	s_add_u32 s6, s26, 0x158000
	global_load_lds_dwordx4 v134, s[26:27]
	s_addc_u32 s7, s27, 0
	s_add_i32 m0, s40, 0x14000
	s_mul_i32 s10, s56, 0x2b0000
	global_load_lds_dwordx4 v130, s[6:7]
	s_add_i32 m0, s40, 0x16000
	v_mul_u32_u24_e32 v11, 0x1580, v5
	s_mul_hi_i32 s8, s56, 0x2b0000
	s_add_u32 s24, s31, s10
	v_or_b32_e32 v5, v1, v11
	v_mul_u32_u24_e32 v12, 0x1580, v2
	s_addc_u32 s25, s33, s8
	s_add_i32 s41, s40, 0x2000
	v_lshlrev_b32_e32 v128, 1, v5
	v_mov_b32_e32 v128, v240
	v_or_b32_e32 v2, v12, v1
	global_load_lds_dwordx4 v134, s[6:7]
	s_mov_b32 m0, s40
	s_add_u32 s6, s24, 0x158000
	v_lshlrev_b32_e32 v132, 1, v2
	v_mov_b32_e32 v132, v241
	global_load_lds_dwordx4 v128, s[24:25]
	s_mov_b32 m0, s41
	s_addc_u32 s7, s25, 0
	s_add_i32 s42, s40, 0x4000
	global_load_lds_dwordx4 v132, s[24:25]
	s_mov_b32 m0, s42
	s_add_i32 s43, s40, 0x6000
	global_load_lds_dwordx4 v128, s[6:7]
	s_mov_b32 m0, s43
	v_mov_b32_e32 v131, 0
	global_load_lds_dwordx4 v132, s[6:7]
	v_mov_b32_e32 v135, v131
	v_mov_b32_e32 v129, v131
	v_mov_b32_e32 v133, v131
	s_cmp_eq_u32 s0, 1
	s_mov_b32 s44, 0
	v_lshl_add_u64 v[6:7], s[26:27], 0, v[130:131]
	v_lshl_add_u64 v[4:5], s[26:27], 0, v[134:135]
	v_lshl_add_u64 v[0:1], s[24:25], 0, v[128:129]
	s_cselect_b64 s[6:7], -1, 0
	s_cmp_lg_u32 s0, 1
	v_lshl_add_u64 v[2:3], s[24:25], 0, v[132:133]
	s_cbranch_scc1 .LBB0_1046
	s_barrier
.LBB0_1046:
	v_readlane_b32 s8, v246, 10
	v_readlane_b32 s9, v246, 11
	s_add_u32 s8, s8, 0x8800000
	s_addc_u32 s9, s9, 0
	s_lshl_b32 s1, s1, 5
	s_mov_b64 s[10:11], 0x80
	s_and_b32 s1, s1, 0x60
	s_add_i32 m0, s40, 0x18000
	v_lshl_add_u64 v[6:7], v[6:7], 0, s[10:11]
	s_lshl_b32 s14, s0, 13
	s_lshl_b32 s15, s1, 7
	s_waitcnt vmcnt(2)
	s_barrier
	global_load_lds_dwordx4 v[6:7], off
	v_lshl_add_u64 v[4:5], v[4:5], 0, s[10:11]
	s_add_i32 m0, s40, 0x1a000
	s_add_i32 s45, s40, 0x8000
	s_add_i32 s46, s40, 0xa000
	global_load_lds_dwordx4 v[4:5], off
	v_lshl_add_u64 v[0:1], v[0:1], 0, s[10:11]
	s_mov_b32 m0, s45
	s_add_u32 s12, s26, 0x158080
	global_load_lds_dwordx4 v[0:1], off
	v_lshl_add_u64 v[0:1], v[2:3], 0, s[10:11]
	s_mov_b32 m0, s46
	s_addc_u32 s13, s27, 0
	global_load_lds_dwordx4 v[0:1], off
	s_add_i32 m0, s40, 0x1c000
	v_lshl_add_u64 v[0:1], s[12:13], 0, v[130:131]
	global_load_lds_dwordx4 v[0:1], off
	v_lshl_add_u64 v[0:1], s[12:13], 0, v[134:135]
	s_add_i32 m0, s40, 0x1e000
	v_lshlrev_b32_e32 v2, 2, v144
	global_load_lds_dwordx4 v[0:1], off
	v_and_b32_e32 v0, 15, v144
	v_lshl_or_b32 v145, s0, 6, v0
	v_lshlrev_b32_e32 v1, 1, v10
	v_lshlrev_b32_e32 v3, 6, v144
	s_movk_i32 s0, 0x3c0
	v_lshl_or_b32 v0, v0, 6, v1
	v_and_b32_e32 v2, 32, v2
	v_and_or_b32 v1, v3, s0, v1
	v_bitop3_b32 v148, s15, v1, v2 bitop3:0xf6
	s_waitcnt vmcnt(6)
	s_cmpk_lt_u32 s2, 0x100
	v_add_u16_e32 v1, v8, v9
	v_bitop3_b32 v0, v0, s14, v2 bitop3:0xde
	s_cselect_b64 s[12:13], -1, 0
	v_lshrrev_b16_e32 v1, 1, v1
	s_add_i32 s48, 0, 0x10000
	s_add_i32 s49, 0, 0x14000
	s_sext_i32_i8 s57, s3
	s_ashr_i32 s47, s34, 31
	v_or_b32_e32 v149, s1, v10
	v_add_lshl_u32 v136, v11, v1, 1
	v_mov_b32_e32 v136, v240
	v_mov_b32_e32 v137, v131
	v_add_lshl_u32 v138, v12, v1, 1
	v_mov_b32_e32 v138, v241
	v_mov_b32_e32 v139, v131
	v_mov_b64_e32 v[140:141], 0x400
	v_mov_b64_e32 v[142:143], 0x3ff
	v_add_u32_e32 v150, s48, v148
	v_add_u32_e32 v151, s49, v148
	v_add_u32_e32 v152, 0, v0
	v_and_b32_e32 v230, 15, v144
	v_bfe_u32 v231, v144, 4, 2
	v_and_b32_e32 v232, 7, v230
	v_xor_b32_e32 v231, v231, v232
	v_lshlrev_b32_e32 v231, 4, v231
	v_lshl_or_b32 v231, v230, 7, v231
	v_lshrrev_b32_e32 v232, 8, v144
	v_lshl_or_b32 v152, v232, 13, v231
	v_xor_b32_e32 v242, 64, v152
	v_bfe_u32 v232, v144, 6, 2
	v_lshl_or_b32 v150, v232, 12, v231
	v_add_u32_e32 v150, 0x10000, v150
	v_xor_b32_e32 v151, 64, v150
	s_mov_b64 s[14:15], 0x80000
	s_mov_b32 s50, 0x80000
	s_mov_b64 s[16:17], 0x90000
	s_mov_b32 s51, 0x90000
	s_mov_b64 s[18:19], 0xa0000
	s_mov_b32 s52, 0xa0000
	s_mov_b64 s[20:21], 0xb0000
	s_mov_b32 s53, 0xb0000
	s_barrier
	s_branch .LBB0_1049

; #define PG8_STAGE(bufoff, gbase, voff) do { _Pragma("unroll") for (int _i = 0; _i < 2; ++_i) \
;         __builtin_amdgcn_global_load_lds((const unsigned*)((const char*)(gbase) + (voff)[_i]), (PG8_LAS unsigned*)(lds + (bufoff) + ldsw + _i * 8192), 16, 0, 0); } while (0)
; #define PG8_LDA(dst, b, h) do { _Pragma("unroll") for (int m = 0; m < 4; ++m) _Pragma("unroll") for (int k = 0; k < 2; ++k) dst[m][k] = *(const PG8_LAS bf16x8*)(lds + PG8_SA(b, h) + aoff + m * 2048 + k * 1024); } while (0)
; #define PG8_LDB(dst, b, h) do { _Pragma("unroll") for (int n = 0; n < 2; ++n) _Pragma("unroll") for (int k = 0; k < 2; ++k) dst[n][k] = *(const PG8_LAS bf16x8*)(lds + PG8_SB(b, h) + boff + n * 2048 + k * 1024); } while (0)
; #define PG8_MMA(ai, bj, At, Bt) do { __builtin_amdgcn_s_setprio(1); _Pragma("unroll") for (int m = 0; m < 4; ++m) _Pragma("unroll") for (int n = 0; n < 2; ++n) _Pragma("unroll") for (int k = 0; k < 2; ++k) \
;         acc[ai][bj][m][n] = __builtin_amdgcn_mfma_f32_16x16x32_bf16(Bt[n][k], At[m][k], acc[ai][bj][m][n], 0, 0, 0); __builtin_amdgcn_s_setprio(0); } while (0)
; #define PG8_WAIT_V(n) asm volatile("s_waitcnt vmcnt(" #n ")" ::: "memory")
; #define PG8_WAIT_L(n) asm volatile("s_waitcnt lgkmcnt(" #n ")" ::: "memory")
; #define PG8_BAR __builtin_amdgcn_s_barrier()
; #define PG8_SCHED __builtin_amdgcn_sched_barrier(0)
; template <class Epi, class Sched, bool ALIGN_EPI = false, bool SP2 = false>
; __device__ __forceinline__ void gemm_phase(PG8_LAS unsigned char* lds, const Gemm g, const Sched& S, const Epi& E) {
;     ...
;             PG8_LDB(B0, 0, 0); PG8_LDB(B1, 0, 1); PG8_SCHED; PG8_LDA(At, 0, 0); PG8_STAGE(PG8_SA(1, 1), a1 + hstep, voffA);
;             PG8_WAIT_V(8); PG8_WAIT_L(0); PG8_BAR; PG8_MMA(0, 0, At, B0); PG8_MMA(0, 1, At, B1); PG8_BAR; PG8_SCHED;
;             PG8_LDA(At, 0, 1); PG8_STAGE(PG8_SB(0, 0), b2, voffB); PG8_STAGE(PG8_SB(0, 1), b2 + hstep, voffB); PG8_STAGE(PG8_SA(0, 0), a2, voffA);
;             PG8_WAIT_V(8); PG8_WAIT_L(0); PG8_BAR; PG8_MMA(1, 0, At, B0); PG8_MMA(1, 1, At, B1); PG8_BAR; PG8_SCHED;
.LBB0_1060:
	ds_read_b128 v[154:157], v150
	ds_read_b128 v[160:163], v151
	ds_read_b128 v[164:167], v150 offset:2048
	ds_read_b128 v[168:171], v151 offset:2048
	ds_read_b128 v[172:175], v150 offset:16384
	ds_read_b128 v[176:179], v151 offset:16384
	ds_read_b128 v[180:183], v150 offset:18432
	ds_read_b128 v[184:187], v151 offset:18432
	s_add_u32 s26, s24, 0xffea8080
	s_addc_u32 s27, s25, -1
	s_cmpk_eq_i32 s60, 0x52
	s_cselect_b32 s29, s3, s27
	s_cselect_b32 s28, s2, s26
	s_cselect_b32 s27, s23, s59
	s_cselect_b32 s26, s22, s58
	v_lshl_add_u64 v[146:147], s[24:25], 0, v[136:137]
	s_add_i32 m0, s40, 0xc000
	ds_read_b128 v[188:191], v152
	ds_read_b128 v[192:195], v242
	ds_read_b128 v[196:199], v152 offset:2048
	ds_read_b128 v[200:203], v242 offset:2048
	ds_read_b128 v[204:207], v152 offset:4096
	ds_read_b128 v[208:211], v242 offset:4096
	ds_read_b128 v[212:215], v152 offset:6144
	ds_read_b128 v[216:219], v242 offset:6144
	global_load_lds_dwordx4 v[146:147], off
	v_lshl_add_u64 v[146:147], s[24:25], 0, v[138:139]
	s_add_i32 m0, s40, 0xe000
	s_nop 0
	global_load_lds_dwordx4 v[146:147], off
	s_waitcnt vmcnt(8)
	s_waitcnt lgkmcnt(0)
	s_barrier
	s_setprio 1
	s_waitcnt lgkmcnt(0)
	v_mfma_f32_16x16x32_bf16 v[124:127], v[154:157], v[188:191], v[124:127]
	v_mfma_f32_16x16x32_bf16 v[120:123], v[164:167], v[188:191], v[120:123]
	v_mfma_f32_16x16x32_bf16 v[116:119], v[154:157], v[196:199], v[116:119]
	v_mfma_f32_16x16x32_bf16 v[108:111], v[164:167], v[196:199], v[108:111]
	v_mfma_f32_16x16x32_bf16 v[100:103], v[154:157], v[204:207], v[100:103]
	v_mfma_f32_16x16x32_bf16 v[92:95], v[164:167], v[204:207], v[92:95]
	v_mfma_f32_16x16x32_bf16 v[84:87], v[154:157], v[212:215], v[84:87]
	v_mfma_f32_16x16x32_bf16 v[76:79], v[164:167], v[212:215], v[76:79]
	v_mfma_f32_16x16x32_bf16 v[124:127], v[160:163], v[192:195], v[124:127]
	v_mfma_f32_16x16x32_bf16 v[120:123], v[168:171], v[192:195], v[120:123]
	v_mfma_f32_16x16x32_bf16 v[116:119], v[160:163], v[200:203], v[116:119]
	v_mfma_f32_16x16x32_bf16 v[108:111], v[168:171], v[200:203], v[108:111]
	v_mfma_f32_16x16x32_bf16 v[100:103], v[160:163], v[208:211], v[100:103]
	v_mfma_f32_16x16x32_bf16 v[92:95], v[168:171], v[208:211], v[92:95]
	v_mfma_f32_16x16x32_bf16 v[84:87], v[160:163], v[216:219], v[84:87]
	v_mfma_f32_16x16x32_bf16 v[76:79], v[168:171], v[216:219], v[76:79]
	s_setprio 0
	s_setprio 1
	v_mfma_f32_16x16x32_bf16 v[112:115], v[172:175], v[188:191], v[112:115]
	v_mfma_f32_16x16x32_bf16 v[104:107], v[180:183], v[188:191], v[104:107]
	v_mfma_f32_16x16x32_bf16 v[96:99], v[172:175], v[196:199], v[96:99]
	v_mfma_f32_16x16x32_bf16 v[88:91], v[180:183], v[196:199], v[88:91]
	v_mfma_f32_16x16x32_bf16 v[80:83], v[172:175], v[204:207], v[80:83]
	v_mfma_f32_16x16x32_bf16 v[72:75], v[180:183], v[204:207], v[72:75]
	v_mfma_f32_16x16x32_bf16 v[68:71], v[172:175], v[212:215], v[68:71]
	v_mfma_f32_16x16x32_bf16 v[64:67], v[180:183], v[212:215], v[64:67]
	v_mfma_f32_16x16x32_bf16 v[112:115], v[176:179], v[192:195], v[112:115]
	v_mfma_f32_16x16x32_bf16 v[104:107], v[184:187], v[192:195], v[104:107]
	v_mfma_f32_16x16x32_bf16 v[96:99], v[176:179], v[200:203], v[96:99]
	v_mfma_f32_16x16x32_bf16 v[88:91], v[184:187], v[200:203], v[88:91]
	v_mfma_f32_16x16x32_bf16 v[80:83], v[176:179], v[208:211], v[80:83]
	v_mfma_f32_16x16x32_bf16 v[72:75], v[184:187], v[208:211], v[72:75]
	v_mfma_f32_16x16x32_bf16 v[68:71], v[176:179], v[216:219], v[68:71]
	v_mfma_f32_16x16x32_bf16 v[64:67], v[184:187], v[216:219], v[64:67]
	s_setprio 0
	s_barrier
	s_add_i32 s36, s48, s39
	v_lshl_add_u64 v[146:147], s[26:27], 0, v[130:131]
	s_mov_b32 m0, s36
	ds_read_b128 v[188:191], v152 offset:16384
	ds_read_b128 v[192:195], v242 offset:16384
	ds_read_b128 v[196:199], v152 offset:18432
	ds_read_b128 v[200:203], v242 offset:18432
	ds_read_b128 v[204:207], v152 offset:20480
	ds_read_b128 v[208:211], v242 offset:20480
	ds_read_b128 v[212:215], v152 offset:22528
	ds_read_b128 v[216:219], v242 offset:22528
	global_load_lds_dwordx4 v[146:147], off
	s_add_i32 m0, s36, 0x2000
	s_add_u32 s36, s26, 0x158000
	v_lshl_add_u64 v[220:221], s[26:27], 0, v[134:135]
	s_addc_u32 s37, s27, 0
	s_add_i32 s61, s49, s39
	global_load_lds_dwordx4 v[220:221], off
	v_lshl_add_u64 v[222:223], s[36:37], 0, v[130:131]
	s_mov_b32 m0, s61
	v_lshl_add_u64 v[224:225], s[28:29], 0, v[132:133]
	global_load_lds_dwordx4 v[222:223], off
	v_lshl_add_u64 v[222:223], s[36:37], 0, v[134:135]
	s_add_i32 m0, s61, 0x2000
	s_nop 0
	global_load_lds_dwordx4 v[222:223], off
	v_lshl_add_u64 v[222:223], s[28:29], 0, v[128:129]
	s_mov_b32 m0, s40
	s_nop 0
	global_load_lds_dwordx4 v[222:223], off
	s_mov_b32 m0, s41
	s_nop 0
	global_load_lds_dwordx4 v[224:225], off
	s_waitcnt vmcnt(8)
	s_waitcnt lgkmcnt(0)
	s_barrier
; #define PG8_STAGE(bufoff, gbase, voff) do { _Pragma("unroll") for (int _i = 0; _i < 2; ++_i) \
;         __builtin_amdgcn_global_load_lds((const unsigned*)((const char*)(gbase) + (voff)[_i]), (PG8_LAS unsigned*)(lds + (bufoff) + ldsw + _i * 8192), 16, 0, 0); } while (0)
; #define PG8_LDA(dst, b, h) do { _Pragma("unroll") for (int m = 0; m < 4; ++m) _Pragma("unroll") for (int k = 0; k < 2; ++k) dst[m][k] = *(const PG8_LAS bf16x8*)(lds + PG8_SA(b, h) + aoff + m * 2048 + k * 1024); } while (0)
; #define PG8_LDB(dst, b, h) do { _Pragma("unroll") for (int n = 0; n < 2; ++n) _Pragma("unroll") for (int k = 0; k < 2; ++k) dst[n][k] = *(const PG8_LAS bf16x8*)(lds + PG8_SB(b, h) + boff + n * 2048 + k * 1024); } while (0)
; #define PG8_MMA(ai, bj, At, Bt) do { __builtin_amdgcn_s_setprio(1); _Pragma("unroll") for (int m = 0; m < 4; ++m) _Pragma("unroll") for (int n = 0; n < 2; ++n) _Pragma("unroll") for (int k = 0; k < 2; ++k) \
;         acc[ai][bj][m][n] = __builtin_amdgcn_mfma_f32_16x16x32_bf16(Bt[n][k], At[m][k], acc[ai][bj][m][n], 0, 0, 0); __builtin_amdgcn_s_setprio(0); } while (0)
; #define PG8_WAIT_V(n) asm volatile("s_waitcnt vmcnt(" #n ")" ::: "memory")
; #define PG8_WAIT_L(n) asm volatile("s_waitcnt lgkmcnt(" #n ")" ::: "memory")
; #define PG8_BAR __builtin_amdgcn_s_barrier()
; #define PG8_SCHED __builtin_amdgcn_sched_barrier(0)
; template <class Epi, class Sched, bool ALIGN_EPI = false, bool SP2 = false>
; __device__ __forceinline__ void gemm_phase(PG8_LAS unsigned char* lds, const Gemm g, const Sched& S, const Epi& E) {
;     ...
;             PG8_WAIT_V(8); PG8_WAIT_L(0); PG8_BAR; PG8_MMA(1, 0, At, B0); PG8_MMA(1, 1, At, B1); PG8_BAR; PG8_SCHED;
;             PG8_LDB(B0, 1, 0); PG8_LDB(B1, 1, 1); PG8_SCHED; PG8_LDA(At, 1, 0); PG8_STAGE(PG8_SA(0, 1), a2 + hstep, voffA);
;             PG8_WAIT_V(8); PG8_WAIT_L(0); PG8_BAR; PG8_MMA(0, 0, At, B0); PG8_MMA(0, 1, At, B1); PG8_BAR; PG8_SCHED;
	s_setprio 1
	s_waitcnt lgkmcnt(0)
	v_mfma_f32_16x16x32_bf16 v[60:63], v[154:157], v[188:191], v[60:63]
	v_mfma_f32_16x16x32_bf16 v[56:59], v[164:167], v[188:191], v[56:59]
	v_mfma_f32_16x16x32_bf16 v[52:55], v[154:157], v[196:199], v[52:55]
	v_mfma_f32_16x16x32_bf16 v[44:47], v[164:167], v[196:199], v[44:47]
	v_mfma_f32_16x16x32_bf16 v[36:39], v[154:157], v[204:207], v[36:39]
	v_mfma_f32_16x16x32_bf16 v[28:31], v[164:167], v[204:207], v[28:31]
	v_mfma_f32_16x16x32_bf16 v[20:23], v[154:157], v[212:215], v[20:23]
	v_mfma_f32_16x16x32_bf16 v[12:15], v[164:167], v[212:215], v[12:15]
	v_mfma_f32_16x16x32_bf16 v[60:63], v[160:163], v[192:195], v[60:63]
	v_mfma_f32_16x16x32_bf16 v[56:59], v[168:171], v[192:195], v[56:59]
	v_mfma_f32_16x16x32_bf16 v[52:55], v[160:163], v[200:203], v[52:55]
	v_mfma_f32_16x16x32_bf16 v[44:47], v[168:171], v[200:203], v[44:47]
	v_mfma_f32_16x16x32_bf16 v[36:39], v[160:163], v[208:211], v[36:39]
	v_mfma_f32_16x16x32_bf16 v[28:31], v[168:171], v[208:211], v[28:31]
	v_mfma_f32_16x16x32_bf16 v[20:23], v[160:163], v[216:219], v[20:23]
	v_mfma_f32_16x16x32_bf16 v[12:15], v[168:171], v[216:219], v[12:15]
	s_setprio 0
	s_setprio 1
	v_mfma_f32_16x16x32_bf16 v[48:51], v[172:175], v[188:191], v[48:51]
	v_mfma_f32_16x16x32_bf16 v[40:43], v[180:183], v[188:191], v[40:43]
	v_mfma_f32_16x16x32_bf16 v[32:35], v[172:175], v[196:199], v[32:35]
	v_mfma_f32_16x16x32_bf16 v[24:27], v[180:183], v[196:199], v[24:27]
	v_mfma_f32_16x16x32_bf16 v[16:19], v[172:175], v[204:207], v[16:19]
	v_mfma_f32_16x16x32_bf16 v[8:11], v[180:183], v[204:207], v[8:11]
	v_mfma_f32_16x16x32_bf16 v[4:7], v[172:175], v[212:215], v[4:7]
	v_mfma_f32_16x16x32_bf16 v[0:3], v[180:183], v[212:215], v[0:3]
	v_mfma_f32_16x16x32_bf16 v[48:51], v[176:179], v[192:195], v[48:51]
	v_mfma_f32_16x16x32_bf16 v[40:43], v[184:187], v[192:195], v[40:43]
	v_mfma_f32_16x16x32_bf16 v[32:35], v[176:179], v[200:203], v[32:35]
	v_mfma_f32_16x16x32_bf16 v[24:27], v[184:187], v[200:203], v[24:27]
	v_mfma_f32_16x16x32_bf16 v[16:19], v[176:179], v[208:211], v[16:19]
	v_mfma_f32_16x16x32_bf16 v[8:11], v[184:187], v[208:211], v[8:11]
	v_mfma_f32_16x16x32_bf16 v[4:7], v[176:179], v[216:219], v[4:7]
	v_mfma_f32_16x16x32_bf16 v[0:3], v[184:187], v[216:219], v[0:3]
	s_setprio 0
	s_barrier
	s_add_i32 s36, 0, 0x18000
	v_add_u32_e32 v153, s36, v148
	s_add_i32 s37, 0, 0x1c000
	ds_read_b128 v[154:157], v150 offset:32768
	ds_read_b128 v[160:163], v151 offset:32768
	ds_read_b128 v[164:167], v150 offset:34816
	ds_read_b128 v[168:171], v151 offset:34816
	v_add_u32_e32 v153, s37, v148
	ds_read_b128 v[172:175], v150 offset:49152
	ds_read_b128 v[176:179], v151 offset:49152
	ds_read_b128 v[180:183], v150 offset:51200
	ds_read_b128 v[184:187], v151 offset:51200
	s_add_u32 s28, s28, 0x158000
	s_addc_u32 s29, s29, 0
	s_mov_b32 m0, s42
	v_lshl_add_u64 v[226:227], s[28:29], 0, v[128:129]
	ds_read_b128 v[188:191], v152 offset:32768
	ds_read_b128 v[192:195], v242 offset:32768
	ds_read_b128 v[196:199], v152 offset:34816
	ds_read_b128 v[200:203], v242 offset:34816
	ds_read_b128 v[204:207], v152 offset:36864
	ds_read_b128 v[208:211], v242 offset:36864
	ds_read_b128 v[212:215], v152 offset:38912
	ds_read_b128 v[216:219], v242 offset:38912
	global_load_lds_dwordx4 v[226:227], off
	v_lshl_add_u64 v[226:227], s[28:29], 0, v[132:133]
	s_mov_b32 m0, s43
	s_nop 0
	global_load_lds_dwordx4 v[226:227], off
	s_waitcnt vmcnt(8)
	s_waitcnt lgkmcnt(0)
	s_barrier
	s_setprio 1
	s_waitcnt lgkmcnt(0)
	v_mfma_f32_16x16x32_bf16 v[124:127], v[154:157], v[188:191], v[124:127]
	v_mfma_f32_16x16x32_bf16 v[120:123], v[164:167], v[188:191], v[120:123]
	v_mfma_f32_16x16x32_bf16 v[116:119], v[154:157], v[196:199], v[116:119]
	v_mfma_f32_16x16x32_bf16 v[108:111], v[164:167], v[196:199], v[108:111]
	v_mfma_f32_16x16x32_bf16 v[100:103], v[154:157], v[204:207], v[100:103]
	v_mfma_f32_16x16x32_bf16 v[92:95], v[164:167], v[204:207], v[92:95]
	v_mfma_f32_16x16x32_bf16 v[84:87], v[154:157], v[212:215], v[84:87]
	v_mfma_f32_16x16x32_bf16 v[76:79], v[164:167], v[212:215], v[76:79]
	v_mfma_f32_16x16x32_bf16 v[124:127], v[160:163], v[192:195], v[124:127]
	v_mfma_f32_16x16x32_bf16 v[120:123], v[168:171], v[192:195], v[120:123]
	v_mfma_f32_16x16x32_bf16 v[116:119], v[160:163], v[200:203], v[116:119]
	v_mfma_f32_16x16x32_bf16 v[108:111], v[168:171], v[200:203], v[108:111]
	v_mfma_f32_16x16x32_bf16 v[100:103], v[160:163], v[208:211], v[100:103]
	v_mfma_f32_16x16x32_bf16 v[92:95], v[168:171], v[208:211], v[92:95]
	v_mfma_f32_16x16x32_bf16 v[84:87], v[160:163], v[216:219], v[84:87]
	v_mfma_f32_16x16x32_bf16 v[76:79], v[168:171], v[216:219], v[76:79]
	s_setprio 0
	s_setprio 1
	v_mfma_f32_16x16x32_bf16 v[112:115], v[172:175], v[188:191], v[112:115]
	v_mfma_f32_16x16x32_bf16 v[104:107], v[180:183], v[188:191], v[104:107]
	v_mfma_f32_16x16x32_bf16 v[96:99], v[172:175], v[196:199], v[96:99]
	v_mfma_f32_16x16x32_bf16 v[88:91], v[180:183], v[196:199], v[88:91]
	v_mfma_f32_16x16x32_bf16 v[80:83], v[172:175], v[204:207], v[80:83]
	v_mfma_f32_16x16x32_bf16 v[72:75], v[180:183], v[204:207], v[72:75]
	v_mfma_f32_16x16x32_bf16 v[68:71], v[172:175], v[212:215], v[68:71]
	v_mfma_f32_16x16x32_bf16 v[64:67], v[180:183], v[212:215], v[64:67]
	v_mfma_f32_16x16x32_bf16 v[112:115], v[176:179], v[192:195], v[112:115]
	v_mfma_f32_16x16x32_bf16 v[104:107], v[184:187], v[192:195], v[104:107]
	v_mfma_f32_16x16x32_bf16 v[96:99], v[176:179], v[200:203], v[96:99]
	v_mfma_f32_16x16x32_bf16 v[88:91], v[184:187], v[200:203], v[88:91]
	v_mfma_f32_16x16x32_bf16 v[80:83], v[176:179], v[208:211], v[80:83]
	v_mfma_f32_16x16x32_bf16 v[72:75], v[184:187], v[208:211], v[72:75]
	v_mfma_f32_16x16x32_bf16 v[68:71], v[176:179], v[216:219], v[68:71]
	v_mfma_f32_16x16x32_bf16 v[64:67], v[184:187], v[216:219], v[64:67]
	s_setprio 0
	s_barrier
; #define PG8_STAGE(bufoff, gbase, voff) do { _Pragma("unroll") for (int _i = 0; _i < 2; ++_i) \
;         __builtin_amdgcn_global_load_lds((const unsigned*)((const char*)(gbase) + (voff)[_i]), (PG8_LAS unsigned*)(lds + (bufoff) + ldsw + _i * 8192), 16, 0, 0); } while (0)
; #define PG8_LDA(dst, b, h) do { _Pragma("unroll") for (int m = 0; m < 4; ++m) _Pragma("unroll") for (int k = 0; k < 2; ++k) dst[m][k] = *(const PG8_LAS bf16x8*)(lds + PG8_SA(b, h) + aoff + m * 2048 + k * 1024); } while (0)
; #define PG8_MMA(ai, bj, At, Bt) do { __builtin_amdgcn_s_setprio(1); _Pragma("unroll") for (int m = 0; m < 4; ++m) _Pragma("unroll") for (int n = 0; n < 2; ++n) _Pragma("unroll") for (int k = 0; k < 2; ++k) \
;         acc[ai][bj][m][n] = __builtin_amdgcn_mfma_f32_16x16x32_bf16(Bt[n][k], At[m][k], acc[ai][bj][m][n], 0, 0, 0); __builtin_amdgcn_s_setprio(0); } while (0)
; #define PG8_WAIT_V(n) asm volatile("s_waitcnt vmcnt(" #n ")" ::: "memory")
; #define PG8_WAIT_L(n) asm volatile("s_waitcnt lgkmcnt(" #n ")" ::: "memory")
; #define PG8_BAR __builtin_amdgcn_s_barrier()
; #define PG8_SCHED __builtin_amdgcn_sched_barrier(0)
; template <class Epi, class Sched, bool ALIGN_EPI = false, bool SP2 = false>
; __device__ __forceinline__ void gemm_phase(PG8_LAS unsigned char* lds, const Gemm g, const Sched& S, const Epi& E) {
;     ...
;         for (int t = 0; t < nt; t += 2) {
;             const bool last = (t == nt - 2);
;     ...
;             PG8_LDA(At, 1, 1); PG8_STAGE(PG8_SB(1, 0), b3, voffB); PG8_STAGE(PG8_SB(1, 1), b3 + hstep, voffB); PG8_STAGE(PG8_SA(1, 0), a3, voffA);
;             PG8_WAIT_V(8); PG8_WAIT_L(0); PG8_BAR; PG8_MMA(1, 0, At, B0); PG8_MMA(1, 1, At, B1); PG8_BAR; PG8_SCHED;
	s_add_i32 s28, s36, s39
	v_lshl_add_u64 v[146:147], v[146:147], 0, s[10:11]
	s_mov_b32 m0, s28
	ds_read_b128 v[188:191], v152 offset:49152
	ds_read_b128 v[192:195], v242 offset:49152
	ds_read_b128 v[196:199], v152 offset:51200
	ds_read_b128 v[200:203], v242 offset:51200
	ds_read_b128 v[204:207], v152 offset:53248
	ds_read_b128 v[208:211], v242 offset:53248
	ds_read_b128 v[212:215], v152 offset:55296
	ds_read_b128 v[216:219], v242 offset:55296
	global_load_lds_dwordx4 v[146:147], off
	s_add_i32 m0, s28, 0x2000
	s_add_u32 s26, s26, 0x158080
	v_lshl_add_u64 v[146:147], v[220:221], 0, s[10:11]
	s_addc_u32 s27, s27, 0
	s_add_i32 s28, s37, s39
	global_load_lds_dwordx4 v[146:147], off
	v_lshl_add_u64 v[146:147], s[26:27], 0, v[130:131]
	s_mov_b32 m0, s28
	s_nop 0
	global_load_lds_dwordx4 v[146:147], off
	v_lshl_add_u64 v[146:147], s[26:27], 0, v[134:135]
	s_add_i32 m0, s28, 0x2000
	s_nop 0
	global_load_lds_dwordx4 v[146:147], off
	v_lshl_add_u64 v[146:147], v[222:223], 0, s[10:11]
	s_mov_b32 m0, s45
	s_nop 0
	global_load_lds_dwordx4 v[146:147], off
	v_lshl_add_u64 v[146:147], v[224:225], 0, s[10:11]
	s_mov_b32 m0, s46
	s_nop 0
	global_load_lds_dwordx4 v[146:147], off
	s_waitcnt vmcnt(8)
	s_waitcnt lgkmcnt(0)
	s_barrier
	s_setprio 1
	s_waitcnt lgkmcnt(0)
	v_mfma_f32_16x16x32_bf16 v[60:63], v[154:157], v[188:191], v[60:63]
	v_mfma_f32_16x16x32_bf16 v[56:59], v[164:167], v[188:191], v[56:59]
	v_mfma_f32_16x16x32_bf16 v[52:55], v[154:157], v[196:199], v[52:55]
	v_mfma_f32_16x16x32_bf16 v[44:47], v[164:167], v[196:199], v[44:47]
	v_mfma_f32_16x16x32_bf16 v[36:39], v[154:157], v[204:207], v[36:39]
	v_mfma_f32_16x16x32_bf16 v[28:31], v[164:167], v[204:207], v[28:31]
	v_mfma_f32_16x16x32_bf16 v[20:23], v[154:157], v[212:215], v[20:23]
	v_mfma_f32_16x16x32_bf16 v[12:15], v[164:167], v[212:215], v[12:15]
	v_mfma_f32_16x16x32_bf16 v[60:63], v[160:163], v[192:195], v[60:63]
	v_mfma_f32_16x16x32_bf16 v[56:59], v[168:171], v[192:195], v[56:59]
	v_mfma_f32_16x16x32_bf16 v[52:55], v[160:163], v[200:203], v[52:55]
	v_mfma_f32_16x16x32_bf16 v[44:47], v[168:171], v[200:203], v[44:47]
	v_mfma_f32_16x16x32_bf16 v[36:39], v[160:163], v[208:211], v[36:39]
	v_mfma_f32_16x16x32_bf16 v[28:31], v[168:171], v[208:211], v[28:31]
	v_mfma_f32_16x16x32_bf16 v[20:23], v[160:163], v[216:219], v[20:23]
	v_mfma_f32_16x16x32_bf16 v[12:15], v[168:171], v[216:219], v[12:15]
	s_setprio 0
	s_setprio 1
	v_mfma_f32_16x16x32_bf16 v[48:51], v[172:175], v[188:191], v[48:51]
	v_mfma_f32_16x16x32_bf16 v[40:43], v[180:183], v[188:191], v[40:43]
	v_mfma_f32_16x16x32_bf16 v[32:35], v[172:175], v[196:199], v[32:35]
	v_mfma_f32_16x16x32_bf16 v[24:27], v[180:183], v[196:199], v[24:27]
	v_mfma_f32_16x16x32_bf16 v[16:19], v[172:175], v[204:207], v[16:19]
	v_mfma_f32_16x16x32_bf16 v[8:11], v[180:183], v[204:207], v[8:11]
	v_mfma_f32_16x16x32_bf16 v[4:7], v[172:175], v[212:215], v[4:7]
	v_mfma_f32_16x16x32_bf16 v[0:3], v[180:183], v[212:215], v[0:3]
	v_mfma_f32_16x16x32_bf16 v[48:51], v[176:179], v[192:195], v[48:51]
	v_mfma_f32_16x16x32_bf16 v[40:43], v[184:187], v[192:195], v[40:43]
	v_mfma_f32_16x16x32_bf16 v[32:35], v[176:179], v[200:203], v[32:35]
	v_mfma_f32_16x16x32_bf16 v[24:27], v[184:187], v[200:203], v[24:27]
	v_mfma_f32_16x16x32_bf16 v[16:19], v[176:179], v[208:211], v[16:19]
	v_mfma_f32_16x16x32_bf16 v[8:11], v[184:187], v[208:211], v[8:11]
	v_mfma_f32_16x16x32_bf16 v[4:7], v[176:179], v[216:219], v[4:7]
	v_mfma_f32_16x16x32_bf16 v[0:3], v[184:187], v[216:219], v[0:3]
	s_setprio 0
	s_barrier
	s_add_i32 s60, s60, 2
	s_add_u32 s24, s24, 0x100
	s_addc_u32 s25, s25, 0
	s_add_u32 s58, s58, 0x100
	s_addc_u32 s59, s59, 0
	s_cmpk_gt_u32 s60, 0x53
	s_cbranch_scc0 .LBB0_1060
	s_and_b64 vcc, exec, s[12:13]
	s_cbranch_vccz .LBB0_1063
	s_barrier
